# prep phase: KV-layout items assigned to waves in reverse order so the waves with 3 conv items get 1 KV item and those with 2 conv items get 2
# speedup vs baseline: 1.0119x; 1.0119x over previous
; #define LAS __attribute__((address_space(3)))
; __device__ __forceinline__ void prep_items(const Ctx& C, int l, int w0, int nw) {
;     ...
;     {
;         const float* rope = (const float*)(C.ws + WS_ROPE);
;         LAS bf16_t* vt = (LAS bf16_t*)(C.lds + C.wave * 4608);
;         const int hi = lane >> 5, dl = lane & 31;
;         for (int it = w0; it < 4 * 512; it += nw) {
;             const int bg = it >> 9, tile = it & 511, b = bg >> 1, g = bg & 1;
;             const size_t tokb = (size_t)b * S_ + 32 * tile;
.LBB0_477:
	s_cmpk_gt_i32 s0, 0x9ff
	v_and_b32_e32 v11, 31, v52
	v_and_b32_e32 v13, 7, v52
	s_cbranch_scc1 .LBB0_512
	s_add_u32 s22, s4, 0x3a00000
	s_mul_i32 s0, s2, 0x1200
	v_lshrrev_b32_e32 v7, 1, v52
	s_addc_u32 s23, s5, 0
	s_add_i32 s3, s0, 0
	v_and_b32_e32 v7, 24, v7
	v_and_b32_e32 v8, 15, v52
	v_lshrrev_b32_e32 v10, 3, v69
	v_lshrrev_b32_e32 v2, 2, v69
	v_lshrrev_b32_e32 v3, 2, v52
	v_mul_u32_u24_e32 v7, 0x90, v7
	v_lshlrev_b32_e32 v8, 1, v8
	s_add_u32 s24, s4, 0x4200000
	v_and_b32_e32 v2, 8, v2
	v_bfe_u32 v18, v69, 3, 2
	v_and_b32_e32 v3, 8, v3
	v_add3_u32 v15, s3, v7, v8
	v_or_b32_e32 v24, 4, v10
	v_or_b32_e32 v26, 16, v10
	v_bitop3_b32 v8, v10, 19, 24 bitop3:0xc8
	s_addc_u32 s25, s5, 0
	v_mov_b32_e32 v43, v1
	v_or_b32_e32 v34, v2, v18
	v_or_b32_e32 v36, v24, v2
	v_and_or_b32 v38, v26, 19, v2
	v_or3_b32 v40, v2, v8, 4
	v_mul_u32_u24_e32 v2, 0x90, v3
	v_lshlrev_b32_e32 v3, 1, v11
	s_add_u32 s34, s4, 0x5200000
	v_lshl_add_u32 v4, v13, 4, s3
	v_and_b32_e32 v16, 32, v0
	v_lshrrev_b32_e32 v0, 4, v52
	v_add3_u32 v17, s3, v2, v3
	v_lshl_add_u64 v[2:3], s[4:5], 0, v[42:43]
	s_mov_b64 s[10:11], 0x4a00000
	s_addc_u32 s35, s5, 0
	s_lshl_b32 s3, s71, 5
	s_lshl_b32 s2, s2, 2
	v_lshlrev_b32_e32 v12, 3, v13
	v_bfe_u32 v5, v52, 1, 2
	v_and_b32_e32 v0, 2, v0
	v_bfe_u32 v6, v52, 2, 1
	v_and_b32_e32 v20, 48, v42
	v_mul_u32_u24_e32 v7, 0x90, v10
	v_lshl_add_u64 v[42:43], v[2:3], 0, s[10:11]
	s_mov_b64 s[10:11], 0x5a00000
	s_add_i32 s6, s3, s2
	s_movk_i32 s2, 0xf800
	v_cmp_lt_u32_e32 vcc, 1, v13
	v_xor_b32_e32 v14, 8, v12
	v_cmp_eq_u32_e64 s[0:1], 0, v13
	v_or_b32_e32 v22, 8, v10
	v_or_b32_e32 v28, 8, v18
	v_or_b32_e32 v30, 24, v10
	v_or_b32_e32 v32, 12, v10
	v_lshl_add_u64 v[44:45], v[2:3], 0, s[10:11]
	v_or3_b32 v19, v6, v0, s2
	v_or_b32_e32 v21, 0xfffff800, v5
	v_add_u32_e32 v23, v4, v7
	s_sub_i32 s9, s46, s8
	s_add_i32 s9, s9, -1
	s_sub_i32 s2, s9, s8
	s_lshl_b32 s2, s2, 2
	s_add_i32 s6, s6, s2
	s_branch .LBB0_480
